# v020 + attention: persistent -mrun SrcC block (no per-tile accumulator init moves); GEMM: accumulator zeroing with v_mov_b64
# speedup vs baseline: 1.0252x; 1.0098x over previous
; #define GAS __attribute__((address_space(1)))
; #define LAS __attribute__((address_space(3)))
; #define GAS __attribute__((address_space(1)))
; DI int otid() { int t = threadIdx.x; asm volatile("" : "+v"(t)); return t; }
; DI int obid() { int b = blockIdx.x; asm volatile("" : "+s"(b)); return b; }
; template <int VAR> DI void phase_attn(LAS unsigned char* lds, const bf16_t* Q, const bf16_t* K, const bf16_t* VT, bf16_t* O) {
;     const int tid = otid(), lane = tid & 63, r32 = lane & 31, hi = lane >> 5; const int wid = __builtin_amdgcn_readfirstlane(tid >> 6);
;     LAS unsigned char* kbuf = lds; LAS unsigned char* vbuf = lds + 2 * KBUF;
;     const int krow0 = tid / 12, kch0 = tid % 12; const int id1 = tid + 512; const int krow1 = id1 / 12, kch1 = id1 % 12; const bool k2 = id1 < 768;
;     const int vd = tid >> 3, vch = tid & 7;
;     const int bid_ = obid(); const bool latin = (gridDim.x == 256);
;     const int nsteps = latin ? 17 : (17 * 256 - bid_ + (int)gridDim.x - 1) / (int)gridDim.x;
;     for (int st = 0; st < nsteps; ++st) {
;         int qb, bh;
;         if (latin) { const int x = bid_ & 7, li = bid_ >> 3, g = li >> 4, i = li & 15; const int base = x * 32 + g * 16;
;             if (st < 16) { bh = base + st; qb = (i + st) % 17; } else { bh = base + i; qb = (i + 16) % 17; } }
;         else { const int u = bid_ + st * (int)gridDim.x; qb = 16 - (u >> 8); bh = u & 255; }
;         const int b = bh >> 4, h = bh & 15; const int q0 = qb * 256;
;         const size_t rowb = (size_t)b * TT;
;         const int qlast = (q0 + 255 < TT - 1) ? q0 + 255 : TT - 1; const int ntiles = (qlast >> 6) + 1;
;         const int qw0 = q0 + 32 * wid; const bool wvalid = qw0 < TT;
;         int my_last = (qw0 + 31) >> 6; if (my_last > ntiles - 1) my_last = ntiles - 1; if (!wvalid) my_last = -1;
;         int tq = qw0 + r32; if (tq > TT - 1) tq = TT - 1;
;         bf16x8 qr[6];
;         { const bf16_t* qp = Q + (rowb + tq) * 1536 + h * 96 + 8 * hi;
; #pragma unroll
;           for (int s = 0; s < 6; ++s) qr[s] = *(GAS const bf16x8*)(qp + 16 * s); }
;         const bf16_t* Kh = K + (size_t)bh * TT * 96; const bf16_t* Vh = VT + (size_t)(bh * 64 + vd) * 4160;
.LBB0_32:
	s_cmp_lt_i32 s13, 1
	s_cbranch_scc1 .LBB0_82
	s_mov_b32 s1, 0x2aaaaaab
	v_mul_hi_i32 v2, v0, s1
	v_lshrrev_b32_e32 v3, 31, v2
	v_ashrrev_i32_e32 v2, 1, v2
	v_add_u32_e32 v145, v2, v3
	v_mul_lo_u32 v2, v145, 12
	v_sub_u32_e32 v3, v0, v2
	v_add_u32_e32 v2, 0x200, v0
	v_mul_hi_i32 v4, v2, s1
	s_movk_i32 s1, 0x100
	v_cmp_gt_i32_e64 s[6:7], s1, v0
	s_lshl_b32 s1, s12, 5
	v_lshrrev_b32_e32 v5, 31, v4
	v_ashrrev_i32_e32 v4, 1, v4
	s_and_b32 s15, s1, 0xe0
	s_ashr_i32 s1, s12, 3
	v_add_u32_e32 v160, v4, v5
	s_and_b32 s1, s1, -16
	v_min_i32_e32 v5, 0x100f, v145
	s_add_i32 s15, s15, s1
	s_ashr_i32 s17, s0, 1
	v_mad_i64_i32 v[136:137], s[0:1], v5, s71, 0
	v_min_i32_e32 v5, 0x100f, v160
	v_mad_i64_i32 v[140:141], s[0:1], v5, s71, 0
	v_mul_lo_u32 v4, v160, 12
	s_movk_i32 s0, 0xd0
	v_sub_u32_e32 v4, v2, v4
	v_ashrrev_i32_e32 v161, 3, v0
	v_mul_lo_u32 v162, v145, s0
	v_mul_lo_u32 v164, v160, s0
	s_movk_i32 s0, 0x90
	v_and_b32_e32 v134, 31, v0
	v_bfe_u32 v1, v0, 5, 1
	v_lshlrev_b32_e32 v138, 3, v3
	v_lshlrev_b32_e32 v142, 3, v4
	v_lshlrev_b32_e32 v163, 4, v3
	v_lshlrev_b32_e32 v166, 4, v4
	v_mul_lo_u32 v3, v161, s0
	v_lshlrev_b32_e32 v4, 4, v0
	v_lshlrev_b32_e32 v0, 3, v0
	v_add_u32_e32 v3, 0, v3
	v_and_b32_e32 v64, 0x70, v4
	v_and_b32_e32 v4, 0x60, v4
	v_and_b32_e32 v0, 8, v0
	v_add3_u32 v168, v3, v4, v0
	v_mul_u32_u24_e32 v0, 0xd0, v134
	v_lshlrev_b32_e32 v3, 4, v1
	v_add3_u32 v169, 0, v0, v3
	v_lshlrev_b32_e32 v0, 6, v134
	v_sub_u32_e32 v170, v169, v0
	v_min_i32_e32 v0, 0xfcf, v145
	v_add_u32_e32 v0, 64, v0
	v_mad_i64_i32 v[148:149], s[0:1], v0, s71, 0
	v_min_i32_e32 v0, 0xfcf, v160
	s_bfe_u32 s14, s12, 0x40003
	v_lshlrev_b32_e32 v2, 3, v1
	v_add_u32_e32 v5, 0, v162
	v_lshlrev_b32_e32 v144, 2, v1
	v_add_u32_e32 v0, 64, v0
	s_or_b32 s16, s14, 16
	s_andn2_b32 s17, s17, 31
	v_ashrrev_i32_e32 v139, 31, v138
	v_ashrrev_i32_e32 v143, 31, v142
	v_add_u32_e32 v165, 0, v164
	v_mov_b32_e32 v135, v65
	v_lshl_add_u64 v[146:147], s[38:39], 0, v[64:65]
	v_mad_i64_i32 v[150:151], s[0:1], v0, s71, 0
	v_or_b32_e32 v252, 2, v144
	v_or_b32_e32 v204, 34, v144
	v_or_b32_e32 v205, 3, v144
	v_or_b32_e32 v171, 35, v144
	s_mov_b32 s18, 0
	v_lshlrev_b32_e32 v64, 1, v2
	v_add_u32_e32 v200, v5, v163
	s_branch .LBB0_38

; #define LAS __attribute__((address_space(3)))
; DI f32x16 mfma32(bf16x8 a, bf16x8 b, f32x16 c) { return __builtin_amdgcn_mfma_f32_32x32x16_bf16(a, b, c, 0, 0, 0); }
; template <int VAR> DI void phase_attn(LAS unsigned char* lds, const bf16_t* Q, const bf16_t* K, const bf16_t* VT, bf16_t* O) {
;     ...
;             if (VAR != 4 && j <= my_last) {
;                 LAS const unsigned char* kb = kbuf + buf * KBUF + r32 * KPITCH + 16 * hi; LAS const unsigned char* vb = vbuf + buf * VBUF + r32 * VPITCH + 16 * hi;
;                 f32x16 p0, p1;
; #pragma unroll
;                 for (int r = 0; r < 16; ++r) { p0[r] = -mrun; p1[r] = -mrun; }
;                 bf16x8 ka[12], va[8];
; #pragma unroll
;                 for (int s = 0; s < 6; ++s) { ka[2 * s] = *(LAS const bf16x8*)(kb + 32 * s); ka[2 * s + 1] = *(LAS const bf16x8*)(kb + 32 * KPITCH + 32 * s); }
; #pragma unroll
;                 for (int f = 0; f < 4; ++f) { va[2 * f] = *(LAS const bf16x8*)(vb + 32 * f); va[2 * f + 1] = *(LAS const bf16x8*)(vb + 32 * VPITCH + 32 * f); }
;                 __builtin_amdgcn_sched_barrier(0);
; #pragma unroll
;                 for (int s = 0; s < 6; ++s) { if (VAR == 2) { p0[s] += __builtin_bit_cast(f32x4, ka[2 * s])[0]; p1[s] += __builtin_bit_cast(f32x4, ka[2 * s + 1])[1]; } else { p0 = mfma32(ka[2 * s], qr[s], p0); p1 = mfma32(ka[2 * s + 1], qr[s], p1); } }
;                 if (64 * j + 63 > qw0) {
;                     const int qa = qw0 + r32, kb0 = 64 * j + 4 * hi;
; #pragma unroll
;                     for (int r = 0; r < 16; ++r) { const int kv = kb0 + (r & 3) + 8 * (r >> 2); if (kv > qa) p0[r] = -INFINITY; if (kv + 32 > qa) p1[r] = -INFINITY; }
.LBB0_51:
	s_ashr_i32 s8, s36, 6
	s_min_i32 s8, s8, s59
	s_cmpk_lt_i32 s36, 0x1010
	s_cselect_b32 s68, s8, -1
	s_cmp_lt_i32 s68, 0
	s_cbranch_scc1 .LBB0_56
	ds_read_b128 v[102:105], v169
	ds_read_b128 v[106:109], v169 offset:32
	ds_read_b128 v[110:113], v169 offset:6656
	ds_read_b128 v[114:117], v169 offset:6688
	ds_read_b128 v[118:121], v169 offset:64
	ds_read_b128 v[122:125], v169 offset:96
	ds_read_b128 v[126:129], v169 offset:6720
	ds_read_b128 v[130:133], v169 offset:6752
	ds_read_b128 v[208:211], v169 offset:128
	ds_read_b128 v[212:215], v169 offset:160
	ds_read_b128 v[216:219], v169 offset:6784
	ds_read_b128 v[220:223], v169 offset:6816
	ds_read_b128 v[60:63], v170 offset:26624
	ds_read_b128 v[52:55], v170 offset:26656
	ds_read_b128 v[56:59], v170 offset:31232
	ds_read_b128 v[48:51], v170 offset:31264
	ds_read_b128 v[44:47], v170 offset:26688
	ds_read_b128 v[36:39], v170 offset:26720
	ds_read_b128 v[40:43], v170 offset:31296
	ds_read_b128 v[32:35], v170 offset:31328
	v_readlane_b32 s40, v253, 32
	v_readlane_b32 s41, v253, 33
	v_readlane_b32 s42, v253, 34
	v_readlane_b32 s43, v253, 35
	v_readlane_b32 s44, v253, 36
	v_readlane_b32 s45, v253, 37
	v_readlane_b32 s46, v253, 38
	v_readlane_b32 s47, v253, 39
	v_readlane_b32 s48, v253, 40
	v_readlane_b32 s49, v253, 41
	v_readlane_b32 s50, v253, 42
	v_readlane_b32 s51, v253, 43
	v_readlane_b32 s52, v253, 44
	v_readlane_b32 s53, v253, 45
	v_readlane_b32 s54, v253, 46
	v_readlane_b32 s55, v253, 47
	s_mov_b32 s41, s40
	s_mov_b32 s42, s40
	s_mov_b32 s43, s40
	s_mov_b32 s44, s40
	s_mov_b32 s45, s40
	s_mov_b32 s46, s40
	s_mov_b32 s47, s40
	s_mov_b32 s48, s40
	s_mov_b32 s49, s40
	s_mov_b32 s50, s40
	s_mov_b32 s51, s40
	s_mov_b32 s52, s40
	s_mov_b32 s53, s40
	s_mov_b32 s54, s40
	s_mov_b32 s55, s40
	v_mov_b64_e32 v[16:17], s[40:41]
	v_mov_b64_e32 v[18:19], s[42:43]
	v_mov_b64_e32 v[20:21], s[44:45]
	v_mov_b64_e32 v[22:23], s[46:47]
	v_mov_b64_e32 v[24:25], s[48:49]
	v_mov_b64_e32 v[26:27], s[50:51]
	v_mov_b64_e32 v[28:29], s[52:53]
	v_mov_b64_e32 v[30:31], s[54:55]
	s_mov_b32 s8, s40
	v_writelane_b32 v253, s8, 32
	s_waitcnt lgkmcnt(14)
	v_mfma_f32_32x32x16_bf16 v[0:15], v[102:105], v[66:69], v[16:31]
	s_cmp_gt_i32 s36, 62
	v_writelane_b32 v253, s9, 33
	v_writelane_b32 v253, s10, 34
	v_writelane_b32 v253, s11, 35
	v_writelane_b32 v253, s12, 36
	v_writelane_b32 v253, s13, 37
	v_writelane_b32 v253, s14, 38
	v_mfma_f32_32x32x16_bf16 v[16:31], v[110:113], v[66:69], v[16:31]
	v_writelane_b32 v253, s15, 39
	v_writelane_b32 v253, s16, 40
	v_writelane_b32 v253, s17, 41
	v_writelane_b32 v253, s18, 42
	v_writelane_b32 v253, s19, 43
	v_writelane_b32 v253, s20, 44
	v_writelane_b32 v253, s21, 45
	v_mfma_f32_32x32x16_bf16 v[0:15], v[106:109], v[70:73], v[0:15]
	v_writelane_b32 v253, s22, 46
	v_writelane_b32 v253, s23, 47
	v_mfma_f32_32x32x16_bf16 v[16:31], v[114:117], v[70:73], v[16:31]
	v_mfma_f32_32x32x16_bf16 v[0:15], v[118:121], v[74:77], v[0:15]
	s_waitcnt lgkmcnt(13)
	v_mfma_f32_32x32x16_bf16 v[16:31], v[126:129], v[74:77], v[16:31]
	v_mfma_f32_32x32x16_bf16 v[0:15], v[122:125], v[78:81], v[0:15]
	s_waitcnt lgkmcnt(12)
	v_mfma_f32_32x32x16_bf16 v[16:31], v[130:133], v[78:81], v[16:31]
	s_waitcnt lgkmcnt(11)
	v_mfma_f32_32x32x16_bf16 v[0:15], v[208:211], v[82:85], v[0:15]
	s_waitcnt lgkmcnt(9)
	v_mfma_f32_32x32x16_bf16 v[16:31], v[216:219], v[82:85], v[16:31]
	v_mfma_f32_32x32x16_bf16 v[0:15], v[212:215], v[86:89], v[0:15]
	s_waitcnt lgkmcnt(8)
	v_mfma_f32_32x32x16_bf16 v[16:31], v[220:223], v[86:89], v[16:31]
	s_cbranch_scc1 .LBB0_54
	v_or_b32_e32 v102, 32, v144
	v_cmp_le_i32_e32 vcc, v102, v201
	v_or_b32_e32 v102, 33, v144
	s_nop 7
	v_cndmask_b32_e32 v16, v167, v16, vcc
	v_cmp_lt_i32_e32 vcc, v144, v201
	s_nop 1
	v_cndmask_b32_e32 v1, v167, v1, vcc
	v_cmp_le_i32_e32 vcc, v144, v201
	s_nop 1
	v_cndmask_b32_e32 v0, v167, v0, vcc
	v_cmp_le_i32_e32 vcc, v102, v201
	s_nop 1
	v_cndmask_b32_e32 v17, v167, v17, vcc
	v_cmp_le_i32_e32 vcc, v252, v201
	s_nop 1
	v_cndmask_b32_e32 v2, v167, v2, vcc
	v_cmp_le_i32_e32 vcc, v204, v201
	s_nop 1
	v_cndmask_b32_e32 v18, v167, v18, vcc
	v_cmp_le_i32_e32 vcc, v205, v201
	s_nop 1
	v_cndmask_b32_e32 v3, v167, v3, vcc
	v_cmp_le_i32_e32 vcc, v171, v201
	s_nop 1
	v_cndmask_b32_e32 v19, v167, v19, vcc
	v_or_b32_e32 v192, 8, v144
	v_cmp_le_i32_e32 vcc, v192, v201
	s_nop 1
	v_cndmask_b32_e32 v4, v167, v4, vcc
	v_or_b32_e32 v192, 40, v144
	v_cmp_le_i32_e32 vcc, v192, v201
	s_nop 1
	v_cndmask_b32_e32 v20, v167, v20, vcc
	v_or_b32_e32 v192, 9, v144
	v_cmp_le_i32_e32 vcc, v192, v201
	s_nop 1
	v_cndmask_b32_e32 v5, v167, v5, vcc
	v_or_b32_e32 v192, 41, v144
	v_cmp_le_i32_e32 vcc, v192, v201
	s_nop 1
	v_cndmask_b32_e32 v21, v167, v21, vcc
	v_or_b32_e32 v192, 10, v144
	v_cmp_le_i32_e32 vcc, v192, v201
	s_nop 1
	v_cndmask_b32_e32 v6, v167, v6, vcc
	v_or_b32_e32 v192, 42, v144
	v_cmp_le_i32_e32 vcc, v192, v201
	s_nop 1
	v_cndmask_b32_e32 v22, v167, v22, vcc
	v_or_b32_e32 v192, 11, v144
	v_cmp_le_i32_e32 vcc, v192, v201
	s_nop 1
	v_cndmask_b32_e32 v7, v167, v7, vcc
	v_or_b32_e32 v192, 43, v144
	v_cmp_le_i32_e32 vcc, v192, v201
	s_nop 1
	v_cndmask_b32_e32 v23, v167, v23, vcc
	v_or_b32_e32 v192, 16, v144
	v_cmp_le_i32_e32 vcc, v192, v201
	s_nop 1
	v_cndmask_b32_e32 v8, v167, v8, vcc
	v_or_b32_e32 v192, 48, v144
	v_cmp_le_i32_e32 vcc, v192, v201
	s_nop 1
	v_cndmask_b32_e32 v24, v167, v24, vcc
	v_or_b32_e32 v192, 17, v144
	v_cmp_le_i32_e32 vcc, v192, v201
	s_nop 1
	v_cndmask_b32_e32 v9, v167, v9, vcc
	v_or_b32_e32 v192, 49, v144
	v_cmp_le_i32_e32 vcc, v192, v201
	s_nop 1
	v_cndmask_b32_e32 v25, v167, v25, vcc
	v_or_b32_e32 v192, 18, v144
	v_cmp_le_i32_e32 vcc, v192, v201
	s_nop 1
	v_cndmask_b32_e32 v10, v167, v10, vcc
	v_or_b32_e32 v192, 50, v144
	v_cmp_le_i32_e32 vcc, v192, v201
	s_nop 1
	v_cndmask_b32_e32 v26, v167, v26, vcc
	v_or_b32_e32 v192, 19, v144
	v_cmp_le_i32_e32 vcc, v192, v201
	s_nop 1
	v_cndmask_b32_e32 v11, v167, v11, vcc
	v_or_b32_e32 v192, 51, v144
	v_cmp_le_i32_e32 vcc, v192, v201
	s_nop 1
	v_cndmask_b32_e32 v27, v167, v27, vcc
	v_or_b32_e32 v192, 24, v144
	v_cmp_le_i32_e32 vcc, v192, v201
	s_nop 1
	v_cndmask_b32_e32 v12, v167, v12, vcc
	v_or_b32_e32 v192, 56, v144
	v_cmp_le_i32_e32 vcc, v192, v201
	s_nop 1
	v_cndmask_b32_e32 v28, v167, v28, vcc
	v_or_b32_e32 v192, 25, v144
	v_cmp_le_i32_e32 vcc, v192, v201
	s_nop 1
	v_cndmask_b32_e32 v13, v167, v13, vcc
	v_or_b32_e32 v192, 57, v144
	v_cmp_le_i32_e32 vcc, v192, v201
	s_nop 1
	v_cndmask_b32_e32 v29, v167, v29, vcc
	v_or_b32_e32 v192, 26, v144
	v_cmp_le_i32_e32 vcc, v192, v201
	s_nop 1
	v_cndmask_b32_e32 v14, v167, v14, vcc
	v_or_b32_e32 v192, 58, v144
	v_cmp_le_i32_e32 vcc, v192, v201
	s_nop 1
	v_cndmask_b32_e32 v30, v167, v30, vcc
	v_or_b32_e32 v192, 27, v144
	v_cmp_le_i32_e32 vcc, v192, v201
	s_nop 1
	v_cndmask_b32_e32 v15, v167, v15, vcc
	v_or_b32_e32 v192, 59, v144
	v_cmp_le_i32_e32 vcc, v192, v201
	s_nop 1
	v_cndmask_b32_e32 v31, v167, v31, vcc

; #define LAS __attribute__((address_space(3)))
; #define ATT_LOAD(j) do { int ra = 64 * (j) + krow0; if (ra > TT - 1) ra = TT - 1; kr0 = *(GAS const u32x4*)(Kh + (size_t)ra * 96 + kch0 * 8); \
;             if (k2) { int rb = 64 * (j) + krow1; if (rb > TT - 1) rb = TT - 1; kr1 = *(GAS const u32x4*)(Kh + (size_t)rb * 96 + kch1 * 8); } \
;             vr = *(GAS const u32x4*)(Vh + 64 * (j) + vch * 8); } while (0)
; template <int VAR> DI void phase_attn(LAS unsigned char* lds, const bf16_t* Q, const bf16_t* K, const bf16_t* VT, bf16_t* O) {
;     ...
;         for (int j = 0; j < ntiles; ++j) {
;             const int buf = j & 1;
;             if (VAR != 3 && j + 1 < ntiles) ATT_LOAD(j + 1);
;             if (VAR != 4 && j <= my_last) {
;                 LAS const unsigned char* kb = kbuf + buf * KBUF + r32 * KPITCH + 16 * hi; LAS const unsigned char* vb = vbuf + buf * VBUF + r32 * VPITCH + 16 * hi;
;                 f32x16 p0, p1;
; #pragma unroll
;                 for (int r = 0; r < 16; ++r) { p0[r] = -mrun; p1[r] = -mrun; }
.LBB0_60:
	s_and_b64 vcc, exec, s[8:9]
	s_waitcnt lgkmcnt(0)
	s_barrier
	s_cbranch_vccnz .LBB0_77
	s_movk_i32 s98, 0x80
	v_xor_b32_e32 v176, 0x80000000, v202
	v_mov_b32_e32 v177, v176
	v_mov_b32_e32 v178, v176
	v_mov_b32_e32 v179, v176
	v_mov_b32_e32 v180, v176
	v_mov_b32_e32 v181, v176
	v_mov_b32_e32 v182, v176
	v_mov_b32_e32 v183, v176
	v_mov_b32_e32 v184, v176
	v_mov_b32_e32 v185, v176
	v_mov_b32_e32 v186, v176
	v_mov_b32_e32 v187, v176
	v_mov_b32_e32 v188, v176
	v_mov_b32_e32 v189, v176
	v_mov_b32_e32 v190, v176
	v_mov_b32_e32 v191, v176
	s_mov_b32 s42, 0
	s_branch .LBB0_64

; #define LAS __attribute__((address_space(3)))
; DI f32x16 mfma32(bf16x8 a, bf16x8 b, f32x16 c) { return __builtin_amdgcn_mfma_f32_32x32x16_bf16(a, b, c, 0, 0, 0); }
; template <int VAR> DI void phase_attn(LAS unsigned char* lds, const bf16_t* Q, const bf16_t* K, const bf16_t* VT, bf16_t* O) {
;     ...
;             if (VAR != 4 && j <= my_last) {
;                 LAS const unsigned char* kb = kbuf + buf * KBUF + r32 * KPITCH + 16 * hi; LAS const unsigned char* vb = vbuf + buf * VBUF + r32 * VPITCH + 16 * hi;
;                 f32x16 p0, p1;
; #pragma unroll
;                 for (int r = 0; r < 16; ++r) { p0[r] = -mrun; p1[r] = -mrun; }
;                 bf16x8 ka[12], va[8];
; #pragma unroll
;                 for (int s = 0; s < 6; ++s) { ka[2 * s] = *(LAS const bf16x8*)(kb + 32 * s); ka[2 * s + 1] = *(LAS const bf16x8*)(kb + 32 * KPITCH + 32 * s); }
; #pragma unroll
;                 for (int f = 0; f < 4; ++f) { va[2 * f] = *(LAS const bf16x8*)(vb + 32 * f); va[2 * f + 1] = *(LAS const bf16x8*)(vb + 32 * VPITCH + 32 * f); }
;                 __builtin_amdgcn_sched_barrier(0);
; #pragma unroll
;                 for (int s = 0; s < 6; ++s) { if (VAR == 2) { p0[s] += __builtin_bit_cast(f32x4, ka[2 * s])[0]; p1[s] += __builtin_bit_cast(f32x4, ka[2 * s + 1])[1]; } else { p0 = mfma32(ka[2 * s], qr[s], p0); p1 = mfma32(ka[2 * s + 1], qr[s], p1); } }
;                 if (64 * j + 63 > qw0) {
;                     const int qa = qw0 + r32, kb0 = 64 * j + 4 * hi;
; #pragma unroll
;                     for (int r = 0; r < 16; ++r) { const int kv = kb0 + (r & 3) + 8 * (r >> 2); if (kv > qa) p0[r] = -INFINITY; if (kv + 32 > qa) p1[r] = -INFINITY; }
;                 }
.LBB0_70:
	s_mul_i32 s9, s8, 0x3400
	v_add_u32_e32 v44, s9, v169
	ds_read_b128 v[208:211], v44
	ds_read_b128 v[212:215], v44 offset:32
	ds_read_b128 v[216:219], v44 offset:6656
	ds_read_b128 v[220:223], v44 offset:6688
	ds_read_b128 v[224:227], v44 offset:64
	ds_read_b128 v[228:231], v44 offset:96
	ds_read_b128 v[232:235], v44 offset:6720
	ds_read_b128 v[236:239], v44 offset:6752
	ds_read_b128 v[240:243], v44 offset:128
	ds_read_b128 v[244:247], v44 offset:160
	ds_read_b128 v[248:251], v44 offset:6784
	ds_read_b128 v[172:175], v44 offset:6816
	s_mul_i32 s43, s8, 0x2400
	v_add_u32_e32 v44, s43, v170
	ds_read_b128 v[130:133], v44 offset:26624
	ds_read_b128 v[122:125], v44 offset:26656
	ds_read_b128 v[126:129], v44 offset:31232
	ds_read_b128 v[118:121], v44 offset:31264
	ds_read_b128 v[114:117], v44 offset:26688
	ds_read_b128 v[106:109], v44 offset:26720
	ds_read_b128 v[110:113], v44 offset:31296
	ds_read_b128 v[102:105], v44 offset:31328
	s_waitcnt lgkmcnt(14)
	s_nop 0
	v_mfma_f32_32x32x16_bf16 v[48:63], v[208:211], v[66:69], v[176:191]
	s_add_i32 s9, s98, -1
	s_cmp_le_i32 s9, s36
	v_mfma_f32_32x32x16_bf16 v[32:47], v[216:219], v[66:69], v[176:191]
	v_mfma_f32_32x32x16_bf16 v[48:63], v[212:215], v[70:73], v[48:63]
	v_mfma_f32_32x32x16_bf16 v[32:47], v[220:223], v[70:73], v[32:47]
	v_mfma_f32_32x32x16_bf16 v[48:63], v[224:227], v[74:77], v[48:63]
	s_waitcnt lgkmcnt(13)
	v_mfma_f32_32x32x16_bf16 v[32:47], v[232:235], v[74:77], v[32:47]
	v_mfma_f32_32x32x16_bf16 v[48:63], v[228:231], v[78:81], v[48:63]
	s_waitcnt lgkmcnt(12)
	v_mfma_f32_32x32x16_bf16 v[32:47], v[236:239], v[78:81], v[32:47]
	s_waitcnt lgkmcnt(11)
	v_mfma_f32_32x32x16_bf16 v[48:63], v[240:243], v[82:85], v[48:63]
	s_waitcnt lgkmcnt(9)
	v_mfma_f32_32x32x16_bf16 v[32:47], v[248:251], v[82:85], v[32:47]
	v_mfma_f32_32x32x16_bf16 v[48:63], v[244:247], v[86:89], v[48:63]
	s_waitcnt lgkmcnt(8)
	v_mfma_f32_32x32x16_bf16 v[32:47], v[172:175], v[86:89], v[32:47]
	s_cbranch_scc1 .LBB0_72
	v_add_u32_e32 v172, s98, v144
	v_subrev_u32_e32 v174, 32, v172
	v_subrev_u32_e32 v173, 64, v172
	v_cmp_le_i32_e32 vcc, v174, v201
	s_nop 6
	v_cndmask_b32_e32 v32, v167, v32, vcc
	v_cmp_lt_i32_e32 vcc, v173, v201
	s_nop 1
	v_cndmask_b32_e32 v49, v167, v49, vcc
	v_cmp_le_i32_e32 vcc, v173, v201
	v_subrev_u32_e32 v173, 31, v172
	s_nop 0
	v_cndmask_b32_e32 v48, v167, v48, vcc
	v_cmp_le_i32_e32 vcc, v173, v201
	v_subrev_u32_e32 v173, 62, v172
	s_nop 0
	v_cndmask_b32_e32 v33, v167, v33, vcc
	v_cmp_le_i32_e32 vcc, v173, v201
	v_subrev_u32_e32 v173, 30, v172
	s_nop 0
	v_cndmask_b32_e32 v50, v167, v50, vcc
	v_cmp_le_i32_e32 vcc, v173, v201
	v_subrev_u32_e32 v173, 61, v172
	s_nop 0
	v_cndmask_b32_e32 v34, v167, v34, vcc
	v_cmp_le_i32_e32 vcc, v173, v201
	v_subrev_u32_e32 v173, 29, v172
	s_nop 0
	v_cndmask_b32_e32 v51, v167, v51, vcc
	v_cmp_le_i32_e32 vcc, v173, v201
	v_subrev_u32_e32 v173, 56, v172
	s_nop 0
	v_cndmask_b32_e32 v35, v167, v35, vcc
	v_cmp_le_i32_e32 vcc, v173, v201
	v_subrev_u32_e32 v173, 24, v172
	s_nop 0
	v_cndmask_b32_e32 v52, v167, v52, vcc
	v_cmp_le_i32_e32 vcc, v173, v201
	v_subrev_u32_e32 v173, 55, v172
	s_nop 0
	v_cndmask_b32_e32 v36, v167, v36, vcc
	v_cmp_le_i32_e32 vcc, v173, v201
	v_subrev_u32_e32 v173, 23, v172
	s_nop 0
	v_cndmask_b32_e32 v53, v167, v53, vcc
	v_cmp_le_i32_e32 vcc, v173, v201
	v_subrev_u32_e32 v173, 54, v172
	s_nop 0
	v_cndmask_b32_e32 v37, v167, v37, vcc
	v_cmp_le_i32_e32 vcc, v173, v201
	v_subrev_u32_e32 v173, 22, v172
	s_nop 0
	v_cndmask_b32_e32 v54, v167, v54, vcc
	v_cmp_le_i32_e32 vcc, v173, v201
	v_subrev_u32_e32 v173, 53, v172
	s_nop 0
	v_cndmask_b32_e32 v38, v167, v38, vcc
	v_cmp_le_i32_e32 vcc, v173, v201
	v_subrev_u32_e32 v173, 21, v172
	s_nop 0
	v_cndmask_b32_e32 v55, v167, v55, vcc
	v_cmp_le_i32_e32 vcc, v173, v201
	v_subrev_u32_e32 v173, 48, v172
	s_nop 0
	v_cndmask_b32_e32 v39, v167, v39, vcc
	v_cmp_le_i32_e32 vcc, v173, v201
	v_add_u32_e32 v173, -16, v172
	s_nop 0
	v_cndmask_b32_e32 v56, v167, v56, vcc
	v_cmp_le_i32_e32 vcc, v173, v201
	v_subrev_u32_e32 v173, 47, v172
	s_nop 0
	v_cndmask_b32_e32 v40, v167, v40, vcc
	v_cmp_le_i32_e32 vcc, v173, v201
	v_add_u32_e32 v173, -15, v172
	s_nop 0
	v_cndmask_b32_e32 v57, v167, v57, vcc
	v_cmp_le_i32_e32 vcc, v173, v201
	v_subrev_u32_e32 v173, 46, v172
	s_nop 0
	v_cndmask_b32_e32 v41, v167, v41, vcc
	v_cmp_le_i32_e32 vcc, v173, v201
	v_add_u32_e32 v173, -14, v172
	s_nop 0
	v_cndmask_b32_e32 v58, v167, v58, vcc
	v_cmp_le_i32_e32 vcc, v173, v201
	v_subrev_u32_e32 v173, 45, v172
	s_nop 0
	v_cndmask_b32_e32 v42, v167, v42, vcc
	v_cmp_le_i32_e32 vcc, v173, v201
	v_add_u32_e32 v173, -13, v172
	s_nop 0
	v_cndmask_b32_e32 v59, v167, v59, vcc
	v_cmp_le_i32_e32 vcc, v173, v201
	v_subrev_u32_e32 v173, 40, v172
	s_nop 0
	v_cndmask_b32_e32 v43, v167, v43, vcc
	v_cmp_le_i32_e32 vcc, v173, v201
	v_add_u32_e32 v173, -8, v172
	s_nop 0
	v_cndmask_b32_e32 v60, v167, v60, vcc
	v_cmp_le_i32_e32 vcc, v173, v201
	v_subrev_u32_e32 v173, 39, v172
	s_nop 0
	v_cndmask_b32_e32 v44, v167, v44, vcc
	v_cmp_le_i32_e32 vcc, v173, v201
	v_add_u32_e32 v173, -7, v172
	s_nop 0
	v_cndmask_b32_e32 v61, v167, v61, vcc
	v_cmp_le_i32_e32 vcc, v173, v201
	v_subrev_u32_e32 v173, 38, v172
	s_nop 0
	v_cndmask_b32_e32 v45, v167, v45, vcc
	v_cmp_le_i32_e32 vcc, v173, v201
	v_add_u32_e32 v173, -6, v172
	s_nop 0
	v_cndmask_b32_e32 v62, v167, v62, vcc
	v_cmp_le_i32_e32 vcc, v173, v201
	v_subrev_u32_e32 v173, 37, v172
	v_add_u32_e32 v172, -5, v172
	v_cndmask_b32_e32 v46, v167, v46, vcc
	v_cmp_le_i32_e32 vcc, v173, v201
	s_nop 1
	v_cndmask_b32_e32 v63, v167, v63, vcc
	v_cmp_le_i32_e32 vcc, v172, v201
	s_nop 1
	v_cndmask_b32_e32 v47, v167, v47, vcc
; DI float half_max(float v) { auto rr = __builtin_amdgcn_permlane32_swap(__float_as_uint(v), __float_as_uint(v), false, false); return fmaxf(__uint_as_float(rr[0]), __uint_as_float(rr[1])); }
; template <int VAR> DI void phase_attn(LAS unsigned char* lds, const bf16_t* Q, const bf16_t* K, const bf16_t* VT, bf16_t* O) {
;     ...
;                 float mx;
;                 { float a_ = __builtin_fmaxf(__builtin_fmaxf(p0[0], p0[1]), p1[0]), b_ = __builtin_fmaxf(__builtin_fmaxf(p0[2], p0[3]), p1[1]); a_ = __builtin_fmaxf(__builtin_fmaxf(a_, p1[2]), p1[3]);
; #pragma unroll
;                   for (int r = 4; r < 16; r += 4) { a_ = __builtin_fmaxf(__builtin_fmaxf(a_, p0[r]), p0[r + 1]); b_ = __builtin_fmaxf(__builtin_fmaxf(b_, p0[r + 2]), p0[r + 3]);
;                       a_ = __builtin_fmaxf(__builtin_fmaxf(a_, p1[r]), p1[r + 1]); b_ = __builtin_fmaxf(__builtin_fmaxf(b_, p1[r + 2]), p1[r + 3]); }
;                   mx = half_max(__builtin_fmaxf(a_, b_)); }
;                 if (j == 0) {
;                     mrun = mx;
; #pragma unroll
;                     for (int r = 0; r < 16; ++r) { p0[r] -= mx; p1[r] -= mx; }
;                 } else if (__any(mx > 0.f)) {
;                     const float dl = __builtin_fmaxf(mx, 0.f); mrun += dl; const float fsc = __builtin_amdgcn_exp2f(-dl); lrun *= fsc;
; #pragma unroll
;                     for (int r = 0; r < 16; ++r) { p0[r] -= dl; p1[r] -= dl; o0[r] *= fsc; o1[r] *= fsc; }
;                 }
.LBB0_72:
	s_nop 8
	v_max_f32_e32 v172, v48, v49
	v_max3_f32 v173, v50, v51, v33
	v_max3_f32 v172, v172, v32, v34
	v_max3_f32 v172, v172, v35, v52
	v_max3_f32 v173, v173, v54, v55
	v_max3_f32 v172, v172, v53, v36
	v_max3_f32 v173, v173, v38, v39
	v_max3_f32 v172, v172, v37, v56
	v_max3_f32 v173, v173, v58, v59
	v_max3_f32 v172, v172, v57, v40
	v_max3_f32 v173, v173, v42, v43
	v_max3_f32 v172, v172, v41, v60
	v_max3_f32 v173, v173, v62, v63
	v_max3_f32 v172, v172, v61, v44
	v_max3_f32 v173, v173, v46, v47
	v_max3_f32 v172, v172, v45, v173
	v_mov_b32_e32 v173, v172
	s_nop 1
	v_permlane32_swap_b32_e32 v172, v173
	v_max_f32_e32 v208, v172, v173
	v_cmp_lt_f32_e32 vcc, 4.0, v208
	s_cbranch_vccz .LBB0_74
	v_max_f32_e32 v172, v208, v208
	v_max_f32_e32 v172, 0, v172
	v_exp_f32_e64 v174, -v172
	v_pk_add_f32 v[48:49], v[48:49], v[172:173] op_sel_hi:[1,0] neg_lo:[0,1] neg_hi:[0,1]
	v_pk_add_f32 v[32:33], v[32:33], v[172:173] op_sel_hi:[1,0] neg_lo:[0,1] neg_hi:[0,1]
	v_pk_add_f32 v[50:51], v[50:51], v[172:173] op_sel_hi:[1,0] neg_lo:[0,1] neg_hi:[0,1]
	v_pk_add_f32 v[34:35], v[34:35], v[172:173] op_sel_hi:[1,0] neg_lo:[0,1] neg_hi:[0,1]
	v_pk_add_f32 v[52:53], v[52:53], v[172:173] op_sel_hi:[1,0] neg_lo:[0,1] neg_hi:[0,1]
	v_pk_add_f32 v[36:37], v[36:37], v[172:173] op_sel_hi:[1,0] neg_lo:[0,1] neg_hi:[0,1]
	v_pk_add_f32 v[54:55], v[54:55], v[172:173] op_sel_hi:[1,0] neg_lo:[0,1] neg_hi:[0,1]
	v_pk_add_f32 v[38:39], v[38:39], v[172:173] op_sel_hi:[1,0] neg_lo:[0,1] neg_hi:[0,1]
	v_pk_add_f32 v[56:57], v[56:57], v[172:173] op_sel_hi:[1,0] neg_lo:[0,1] neg_hi:[0,1]
	v_pk_add_f32 v[40:41], v[40:41], v[172:173] op_sel_hi:[1,0] neg_lo:[0,1] neg_hi:[0,1]
	v_pk_add_f32 v[58:59], v[58:59], v[172:173] op_sel_hi:[1,0] neg_lo:[0,1] neg_hi:[0,1]
	v_pk_add_f32 v[42:43], v[42:43], v[172:173] op_sel_hi:[1,0] neg_lo:[0,1] neg_hi:[0,1]
	v_pk_add_f32 v[60:61], v[60:61], v[172:173] op_sel_hi:[1,0] neg_lo:[0,1] neg_hi:[0,1]
	v_pk_add_f32 v[44:45], v[44:45], v[172:173] op_sel_hi:[1,0] neg_lo:[0,1] neg_hi:[0,1]
	v_pk_add_f32 v[62:63], v[62:63], v[172:173] op_sel_hi:[1,0] neg_lo:[0,1] neg_hi:[0,1]
	v_pk_add_f32 v[46:47], v[46:47], v[172:173] op_sel_hi:[1,0] neg_lo:[0,1] neg_hi:[0,1]
	v_pk_mul_f32 v[14:15], v[14:15], v[174:175] op_sel_hi:[1,0]
	v_pk_mul_f32 v[12:13], v[12:13], v[174:175] op_sel_hi:[1,0]
	v_pk_mul_f32 v[10:11], v[10:11], v[174:175] op_sel_hi:[1,0]
	v_pk_mul_f32 v[8:9], v[8:9], v[174:175] op_sel_hi:[1,0]
	v_pk_mul_f32 v[6:7], v[6:7], v[174:175] op_sel_hi:[1,0]
	v_pk_mul_f32 v[4:5], v[4:5], v[174:175] op_sel_hi:[1,0]
	v_pk_mul_f32 v[2:3], v[2:3], v[174:175] op_sel_hi:[1,0]
	v_pk_mul_f32 v[0:1], v[0:1], v[174:175] op_sel_hi:[1,0]
	v_pk_mul_f32 v[30:31], v[30:31], v[174:175] op_sel_hi:[1,0]
	v_pk_mul_f32 v[28:29], v[28:29], v[174:175] op_sel_hi:[1,0]
	v_pk_mul_f32 v[26:27], v[26:27], v[174:175] op_sel_hi:[1,0]
	v_pk_mul_f32 v[24:25], v[24:25], v[174:175] op_sel_hi:[1,0]
	v_pk_mul_f32 v[22:23], v[22:23], v[174:175] op_sel_hi:[1,0]
	v_pk_mul_f32 v[20:21], v[20:21], v[174:175] op_sel_hi:[1,0]
	v_pk_mul_f32 v[18:19], v[18:19], v[174:175] op_sel_hi:[1,0]
	v_pk_mul_f32 v[16:17], v[16:17], v[174:175] op_sel_hi:[1,0]
	v_add_f32_e32 v202, v202, v172
	v_mul_f32_e32 v203, v203, v174
	v_xor_b32_e32 v176, 0x80000000, v202
	v_mov_b32_e32 v177, v176
	v_mov_b32_e32 v178, v176
	v_mov_b32_e32 v179, v176
	v_mov_b32_e32 v180, v176
	v_mov_b32_e32 v181, v176
	v_mov_b32_e32 v182, v176
	v_mov_b32_e32 v183, v176
	v_mov_b32_e32 v184, v176
	v_mov_b32_e32 v185, v176
	v_mov_b32_e32 v186, v176
	v_mov_b32_e32 v187, v176
	v_mov_b32_e32 v188, v176
	v_mov_b32_e32 v189, v176
	v_mov_b32_e32 v190, v176
	v_mov_b32_e32 v191, v176

; template <class Epi, class Sched, bool ALIGN_EPI = false, bool SP2 = false>
; __device__ __forceinline__ void gemm_phase(PG8_LAS unsigned char* lds, const Gemm g, const Sched& S, const Epi& E) {
;     ...
;         if (!has_next) break;
; #pragma unroll
;         for (int a = 0; a < 2; ++a)
; #pragma unroll
;             for (int b = 0; b < 2; ++b)
; #pragma unroll
;                 for (int m = 0; m < 4; ++m)
; #pragma unroll
;                     for (int n = 0; n < 2; ++n) acc[a][b][m][n] = (f32x4){0.f, 0.f, 0.f, 0.f};
;         cur = nxt; cA = nA; cB = nB; ++ui;
.LBB0_205:
	v_readlane_b32 s28, v255, 0
	v_readlane_b32 s29, v255, 1
	s_andn2_b64 vcc, exec, s[28:29]
	s_cbranch_vccnz .LBB0_208
	s_add_u32 s28, s6, 0x100
	s_addc_u32 s29, s7, 0
	s_add_u32 s6, s16, 0x80
	v_mov_b32_e32 v0, 0
	v_mov_b32_e32 v1, 0
	s_addc_u32 s7, s17, 0
	s_mov_b32 s16, 0
	v_mov_b64_e32 v[2:3], v[0:1]
	v_mov_b64_e32 v[4:5], v[0:1]
	v_mov_b64_e32 v[6:7], v[0:1]
	v_mov_b64_e32 v[16:17], v[0:1]
	v_mov_b64_e32 v[18:19], v[0:1]
	v_mov_b64_e32 v[20:21], v[0:1]
	v_mov_b64_e32 v[22:23], v[0:1]
	v_mov_b64_e32 v[32:33], v[0:1]
	v_mov_b64_e32 v[34:35], v[0:1]
	v_mov_b64_e32 v[36:37], v[0:1]
	v_mov_b64_e32 v[38:39], v[0:1]
	v_mov_b64_e32 v[48:49], v[0:1]
	v_mov_b64_e32 v[50:51], v[0:1]
	v_mov_b64_e32 v[52:53], v[0:1]
	v_mov_b64_e32 v[54:55], v[0:1]
	v_mov_b64_e32 v[8:9], v[0:1]
	v_mov_b64_e32 v[10:11], v[0:1]
	v_mov_b64_e32 v[12:13], v[0:1]
	v_mov_b64_e32 v[14:15], v[0:1]
	v_mov_b64_e32 v[24:25], v[0:1]
	v_mov_b64_e32 v[26:27], v[0:1]
	v_mov_b64_e32 v[28:29], v[0:1]
	v_mov_b64_e32 v[30:31], v[0:1]
	v_mov_b64_e32 v[40:41], v[0:1]
	v_mov_b64_e32 v[42:43], v[0:1]
	v_mov_b64_e32 v[44:45], v[0:1]
	v_mov_b64_e32 v[46:47], v[0:1]
	v_mov_b64_e32 v[56:57], v[0:1]
	v_mov_b64_e32 v[58:59], v[0:1]
	v_mov_b64_e32 v[60:61], v[0:1]
	v_mov_b64_e32 v[62:63], v[0:1]
	v_mov_b64_e32 v[68:69], v[0:1]
	v_mov_b64_e32 v[70:71], v[0:1]
	v_mov_b64_e32 v[72:73], v[0:1]
	v_mov_b64_e32 v[74:75], v[0:1]
	v_mov_b64_e32 v[84:85], v[0:1]
	v_mov_b64_e32 v[86:87], v[0:1]
	v_mov_b64_e32 v[88:89], v[0:1]
	s_waitcnt vmcnt(0)
	v_mov_b64_e32 v[90:91], v[0:1]
	v_mov_b64_e32 v[100:101], v[0:1]
	v_mov_b64_e32 v[102:103], v[0:1]
	v_mov_b64_e32 v[104:105], v[0:1]
	v_mov_b64_e32 v[106:107], v[0:1]
	v_mov_b64_e32 v[116:117], v[0:1]
	v_mov_b64_e32 v[118:119], v[0:1]
	v_mov_b64_e32 v[120:121], v[0:1]
	v_mov_b64_e32 v[122:123], v[0:1]
	v_mov_b64_e32 v[76:77], v[0:1]
	v_mov_b64_e32 v[78:79], v[0:1]
	v_mov_b64_e32 v[80:81], v[0:1]
	v_mov_b64_e32 v[82:83], v[0:1]
	v_mov_b64_e32 v[92:93], v[0:1]
	v_mov_b64_e32 v[94:95], v[0:1]
	v_mov_b64_e32 v[96:97], v[0:1]
	v_mov_b64_e32 v[98:99], v[0:1]
	v_mov_b64_e32 v[108:109], v[0:1]
	v_mov_b64_e32 v[110:111], v[0:1]
	v_mov_b64_e32 v[112:113], v[0:1]
	v_mov_b64_e32 v[114:115], v[0:1]
	v_mov_b64_e32 v[124:125], v[0:1]
	v_mov_b64_e32 v[126:127], v[0:1]
	v_mov_b64_e32 v[128:129], v[0:1]
	v_mov_b64_e32 v[130:131], v[0:1]
	v_add_u32_e32 v236, 0x10000, v209
	v_add_u32_e32 v237, 0x14000, v209
	v_add_u32_e32 v238, 0x18000, v209
	v_add_u32_e32 v239, 0x1c000, v209
